# plus: norm1 sample-row slab loads issued together (was 16 serial load-wait-add steps); mix2 scan loads of a pass no longer separated by full waits
# baseline (speedup 1.0000x reference)
.LBB0_321:
	v_add_co_u32_e32 v184, vcc, 0x400000, v26
	s_nop 1
	v_addc_co_u32_e32 v185, vcc, 0, v27, vcc
	global_load_dwordx2 v[184:185], v[184:185], off
	v_add_co_u32_e32 v186, vcc, 0x600000, v26
	s_nop 1
	v_addc_co_u32_e32 v187, vcc, 0, v27, vcc
	global_load_dwordx2 v[186:187], v[186:187], off
	v_add_co_u32_e32 v188, vcc, 0x800000, v26
	s_nop 1
	v_addc_co_u32_e32 v189, vcc, 0, v27, vcc
	global_load_dwordx2 v[188:189], v[188:189], off
	v_add_co_u32_e32 v190, vcc, 0xa00000, v26
	s_nop 1
	v_addc_co_u32_e32 v191, vcc, 0, v27, vcc
	global_load_dwordx2 v[190:191], v[190:191], off
	v_add_co_u32_e32 v192, vcc, 0xc00000, v26
	s_nop 1
	v_addc_co_u32_e32 v193, vcc, 0, v27, vcc
	global_load_dwordx2 v[192:193], v[192:193], off
	v_add_co_u32_e32 v194, vcc, 0xe00000, v26
	s_nop 1
	v_addc_co_u32_e32 v195, vcc, 0, v27, vcc
	global_load_dwordx2 v[194:195], v[194:195], off
	v_add_co_u32_e32 v196, vcc, 0x1000000, v26
	s_nop 1
	v_addc_co_u32_e32 v197, vcc, 0, v27, vcc
	global_load_dwordx2 v[196:197], v[196:197], off
	v_add_co_u32_e32 v198, vcc, 0x1200000, v26
	s_nop 1
	v_addc_co_u32_e32 v199, vcc, 0, v27, vcc
	global_load_dwordx2 v[198:199], v[198:199], off
	v_add_co_u32_e32 v200, vcc, 0x1400000, v26
	s_nop 1
	v_addc_co_u32_e32 v201, vcc, 0, v27, vcc
	global_load_dwordx2 v[200:201], v[200:201], off
	v_add_co_u32_e32 v202, vcc, 0x1600000, v26
	s_nop 1
	v_addc_co_u32_e32 v203, vcc, 0, v27, vcc
	global_load_dwordx2 v[202:203], v[202:203], off
	v_add_co_u32_e32 v204, vcc, 0x1800000, v26
	s_nop 1
	v_addc_co_u32_e32 v205, vcc, 0, v27, vcc
	global_load_dwordx2 v[204:205], v[204:205], off
	v_add_co_u32_e32 v206, vcc, 0x1a00000, v26
	s_nop 1
	v_addc_co_u32_e32 v207, vcc, 0, v27, vcc
	global_load_dwordx2 v[206:207], v[206:207], off
	v_add_co_u32_e32 v208, vcc, 0x1c00000, v26
	s_nop 1
	v_addc_co_u32_e32 v209, vcc, 0, v27, vcc
	global_load_dwordx2 v[208:209], v[208:209], off
	v_add_co_u32_e32 v210, vcc, 0x1e00000, v26
	s_nop 1
	v_addc_co_u32_e32 v211, vcc, 0, v27, vcc
	global_load_dwordx2 v[210:211], v[210:211], off
	s_mov_b32 s0, 0x200000
	v_add_co_u32_e32 v36, vcc, s0, v26
	global_load_dwordx2 v[12:13], v[26:27], off
	s_nop 0
	v_addc_co_u32_e32 v37, vcc, 0, v27, vcc
	global_load_dwordx2 v[36:37], v[36:37], off
	v_lshl_add_u64 v[10:11], s[12:13], 1, v[24:25]
	v_readlane_b32 s10, v252, 31
	v_readlane_b32 s11, v252, 32
	s_waitcnt vmcnt(1)
	v_cvt_f32_f16_sdwa v31, v12 dst_sel:DWORD dst_unused:UNUSED_PAD src0_sel:WORD_1
	v_cvt_f32_f16_sdwa v33, v13 dst_sel:DWORD dst_unused:UNUSED_PAD src0_sel:WORD_1
	v_cvt_f32_f16_e32 v30, v12
	v_cvt_f32_f16_e32 v32, v13
	s_waitcnt vmcnt(0)
	v_cvt_f32_f16_e32 v40, v36
	v_cvt_f32_f16_sdwa v41, v36 dst_sel:DWORD dst_unused:UNUSED_PAD src0_sel:WORD_1
	v_cvt_f32_f16_e32 v38, v37
	v_cvt_f32_f16_sdwa v39, v37 dst_sel:DWORD dst_unused:UNUSED_PAD src0_sel:WORD_1
	v_pk_add_f32 v[12:13], v[32:33], 0 op_sel_hi:[1,0]
	v_pk_add_f32 v[32:33], v[30:31], 0 op_sel_hi:[1,0]
	global_load_dwordx2 v[30:31], v[10:11], off
	v_pk_add_f32 v[36:37], v[32:33], v[40:41]
	v_add_co_u32_e32 v32, vcc, s0, v10
	s_mov_b32 s0, 0x400000
	s_nop 0
	v_addc_co_u32_e32 v33, vcc, 0, v11, vcc
	v_pk_add_f32 v[12:13], v[12:13], v[38:39]
	v_add_co_u32_e32 v38, vcc, s0, v26
	global_load_dwordx2 v[32:33], v[32:33], off
	s_nop 0
	v_addc_co_u32_e32 v39, vcc, 0, v27, vcc
	v_mov_b32_e32 v38, v184
	v_mov_b32_e32 v39, v185
	v_cvt_f32_f16_e32 v40, v38
	v_cvt_f32_f16_sdwa v41, v38 dst_sel:DWORD dst_unused:UNUSED_PAD src0_sel:WORD_1
	v_cvt_f32_f16_e32 v38, v39
	v_cvt_f32_f16_sdwa v39, v39 dst_sel:DWORD dst_unused:UNUSED_PAD src0_sel:WORD_1
	v_pk_add_f32 v[12:13], v[12:13], v[38:39]
	v_pk_add_f32 v[38:39], v[36:37], v[40:41]
	v_add_co_u32_e32 v36, vcc, s0, v10
	s_mov_b32 s0, 0x600000
	s_nop 0
	v_addc_co_u32_e32 v37, vcc, 0, v11, vcc
	v_add_co_u32_e32 v40, vcc, s0, v26
	global_load_dwordx2 v[36:37], v[36:37], off
	s_nop 0
	v_addc_co_u32_e32 v41, vcc, 0, v27, vcc
	v_mov_b32_e32 v40, v186
	v_mov_b32_e32 v41, v187
	v_cvt_f32_f16_e32 v44, v40
	v_cvt_f32_f16_sdwa v45, v40 dst_sel:DWORD dst_unused:UNUSED_PAD src0_sel:WORD_1
	v_cvt_f32_f16_e32 v42, v41
	v_cvt_f32_f16_sdwa v43, v41 dst_sel:DWORD dst_unused:UNUSED_PAD src0_sel:WORD_1
	v_pk_add_f32 v[40:41], v[38:39], v[44:45]
	v_add_co_u32_e32 v38, vcc, s0, v10
	s_mov_b32 s0, 0x800000
	s_nop 0
	v_addc_co_u32_e32 v39, vcc, 0, v11, vcc
	v_pk_add_f32 v[12:13], v[12:13], v[42:43]
	v_add_co_u32_e32 v42, vcc, s0, v26
	global_load_dwordx2 v[38:39], v[38:39], off
	s_nop 0
	v_addc_co_u32_e32 v43, vcc, 0, v27, vcc
	v_mov_b32_e32 v42, v188
	v_mov_b32_e32 v43, v189
	v_cvt_f32_f16_e32 v44, v42
	v_cvt_f32_f16_sdwa v45, v42 dst_sel:DWORD dst_unused:UNUSED_PAD src0_sel:WORD_1
	v_cvt_f32_f16_e32 v42, v43
	v_cvt_f32_f16_sdwa v43, v43 dst_sel:DWORD dst_unused:UNUSED_PAD src0_sel:WORD_1
	v_pk_add_f32 v[12:13], v[12:13], v[42:43]
	v_pk_add_f32 v[42:43], v[40:41], v[44:45]
	v_add_co_u32_e32 v40, vcc, s0, v10
	s_mov_b32 s0, 0xa00000
	s_nop 0
	v_addc_co_u32_e32 v41, vcc, 0, v11, vcc
	v_add_co_u32_e32 v44, vcc, s0, v26
	global_load_dwordx2 v[40:41], v[40:41], off
	s_nop 0
	v_addc_co_u32_e32 v45, vcc, 0, v27, vcc
	v_mov_b32_e32 v44, v190
	v_mov_b32_e32 v45, v191
	v_cvt_f32_f16_e32 v48, v44
	v_cvt_f32_f16_sdwa v49, v44 dst_sel:DWORD dst_unused:UNUSED_PAD src0_sel:WORD_1
	v_cvt_f32_f16_e32 v46, v45
	v_cvt_f32_f16_sdwa v47, v45 dst_sel:DWORD dst_unused:UNUSED_PAD src0_sel:WORD_1
	v_pk_add_f32 v[44:45], v[42:43], v[48:49]
	v_add_co_u32_e32 v42, vcc, s0, v10
	s_mov_b32 s0, 0xc00000
	s_nop 0
	v_addc_co_u32_e32 v43, vcc, 0, v11, vcc
	v_pk_add_f32 v[12:13], v[12:13], v[46:47]
	v_add_co_u32_e32 v46, vcc, s0, v26
	global_load_dwordx2 v[42:43], v[42:43], off
	s_nop 0
	v_addc_co_u32_e32 v47, vcc, 0, v27, vcc
	v_mov_b32_e32 v46, v192
	v_mov_b32_e32 v47, v193
	v_cvt_f32_f16_e32 v48, v46
	v_cvt_f32_f16_sdwa v49, v46 dst_sel:DWORD dst_unused:UNUSED_PAD src0_sel:WORD_1
	v_cvt_f32_f16_e32 v46, v47
	v_cvt_f32_f16_sdwa v47, v47 dst_sel:DWORD dst_unused:UNUSED_PAD src0_sel:WORD_1
	v_pk_add_f32 v[12:13], v[12:13], v[46:47]
	v_pk_add_f32 v[46:47], v[44:45], v[48:49]
	v_add_co_u32_e32 v44, vcc, s0, v10
	s_mov_b32 s0, 0xe00000
	s_nop 0
	v_addc_co_u32_e32 v45, vcc, 0, v11, vcc
	v_add_co_u32_e32 v48, vcc, s0, v26
	global_load_dwordx2 v[44:45], v[44:45], off
	s_nop 0
	v_addc_co_u32_e32 v49, vcc, 0, v27, vcc
	v_mov_b32_e32 v48, v194
	v_mov_b32_e32 v49, v195
	v_cvt_f32_f16_e32 v52, v48
	v_cvt_f32_f16_sdwa v53, v48 dst_sel:DWORD dst_unused:UNUSED_PAD src0_sel:WORD_1
	v_cvt_f32_f16_e32 v50, v49
	v_cvt_f32_f16_sdwa v51, v49 dst_sel:DWORD dst_unused:UNUSED_PAD src0_sel:WORD_1
	v_pk_add_f32 v[48:49], v[46:47], v[52:53]
	v_add_co_u32_e32 v46, vcc, s0, v10
	s_mov_b32 s0, 0x1000000
	s_nop 0
	v_addc_co_u32_e32 v47, vcc, 0, v11, vcc
	v_pk_add_f32 v[12:13], v[12:13], v[50:51]
	v_add_co_u32_e32 v50, vcc, s0, v26
	global_load_dwordx2 v[46:47], v[46:47], off
	s_nop 0
	v_addc_co_u32_e32 v51, vcc, 0, v27, vcc
	v_mov_b32_e32 v50, v196
	v_mov_b32_e32 v51, v197
	v_cvt_f32_f16_e32 v52, v50
	v_cvt_f32_f16_sdwa v53, v50 dst_sel:DWORD dst_unused:UNUSED_PAD src0_sel:WORD_1
	v_cvt_f32_f16_e32 v50, v51
	v_cvt_f32_f16_sdwa v51, v51 dst_sel:DWORD dst_unused:UNUSED_PAD src0_sel:WORD_1
	v_pk_add_f32 v[12:13], v[12:13], v[50:51]
	v_pk_add_f32 v[50:51], v[48:49], v[52:53]
	v_add_co_u32_e32 v48, vcc, s0, v10
	s_mov_b32 s0, 0x1200000
	s_nop 0
	v_addc_co_u32_e32 v49, vcc, 0, v11, vcc
	v_add_co_u32_e32 v52, vcc, s0, v26
	global_load_dwordx2 v[48:49], v[48:49], off
	s_nop 0
	v_addc_co_u32_e32 v53, vcc, 0, v27, vcc
	v_mov_b32_e32 v52, v198
	v_mov_b32_e32 v53, v199
	v_cvt_f32_f16_e32 v56, v52
	v_cvt_f32_f16_sdwa v57, v52 dst_sel:DWORD dst_unused:UNUSED_PAD src0_sel:WORD_1
	v_cvt_f32_f16_e32 v54, v53
	v_cvt_f32_f16_sdwa v55, v53 dst_sel:DWORD dst_unused:UNUSED_PAD src0_sel:WORD_1
	v_pk_add_f32 v[52:53], v[50:51], v[56:57]
	v_add_co_u32_e32 v50, vcc, s0, v10
	s_mov_b32 s0, 0x1400000
	s_nop 0
	v_addc_co_u32_e32 v51, vcc, 0, v11, vcc
	v_pk_add_f32 v[12:13], v[12:13], v[54:55]
	v_add_co_u32_e32 v54, vcc, s0, v26
	global_load_dwordx2 v[50:51], v[50:51], off
	s_nop 0
	v_addc_co_u32_e32 v55, vcc, 0, v27, vcc
	v_mov_b32_e32 v54, v200
	v_mov_b32_e32 v55, v201
	v_cvt_f32_f16_e32 v56, v54
	v_cvt_f32_f16_sdwa v57, v54 dst_sel:DWORD dst_unused:UNUSED_PAD src0_sel:WORD_1
	v_cvt_f32_f16_e32 v54, v55
	v_cvt_f32_f16_sdwa v55, v55 dst_sel:DWORD dst_unused:UNUSED_PAD src0_sel:WORD_1
	v_pk_add_f32 v[12:13], v[12:13], v[54:55]
	v_pk_add_f32 v[54:55], v[52:53], v[56:57]
	v_add_co_u32_e32 v52, vcc, s0, v10
	s_mov_b32 s0, 0x1600000
	s_nop 0
	v_addc_co_u32_e32 v53, vcc, 0, v11, vcc
	v_add_co_u32_e32 v56, vcc, s0, v26
	global_load_dwordx2 v[52:53], v[52:53], off
	s_nop 0
	v_addc_co_u32_e32 v57, vcc, 0, v27, vcc
	v_mov_b32_e32 v56, v202
	v_mov_b32_e32 v57, v203
	v_cvt_f32_f16_e32 v60, v56
	v_cvt_f32_f16_sdwa v61, v56 dst_sel:DWORD dst_unused:UNUSED_PAD src0_sel:WORD_1
	v_cvt_f32_f16_e32 v58, v57
	v_cvt_f32_f16_sdwa v59, v57 dst_sel:DWORD dst_unused:UNUSED_PAD src0_sel:WORD_1
	v_pk_add_f32 v[56:57], v[54:55], v[60:61]
	v_add_co_u32_e32 v54, vcc, s0, v10
	s_mov_b32 s0, 0x1800000
	s_nop 0
	v_addc_co_u32_e32 v55, vcc, 0, v11, vcc
	v_pk_add_f32 v[12:13], v[12:13], v[58:59]
	v_add_co_u32_e32 v58, vcc, s0, v26
	global_load_dwordx2 v[54:55], v[54:55], off
	s_nop 0
	v_addc_co_u32_e32 v59, vcc, 0, v27, vcc
	v_mov_b32_e32 v58, v204
	v_mov_b32_e32 v59, v205
	v_cvt_f32_f16_e32 v60, v58
	v_cvt_f32_f16_sdwa v61, v58 dst_sel:DWORD dst_unused:UNUSED_PAD src0_sel:WORD_1
	v_cvt_f32_f16_e32 v58, v59
	v_cvt_f32_f16_sdwa v59, v59 dst_sel:DWORD dst_unused:UNUSED_PAD src0_sel:WORD_1
	v_pk_add_f32 v[12:13], v[12:13], v[58:59]
	v_pk_add_f32 v[58:59], v[56:57], v[60:61]
	v_add_co_u32_e32 v56, vcc, s0, v10
	s_mov_b32 s0, 0x1a00000
	s_nop 0
	v_addc_co_u32_e32 v57, vcc, 0, v11, vcc
	v_add_co_u32_e32 v60, vcc, s0, v26
	global_load_dwordx2 v[56:57], v[56:57], off
	s_nop 0
	v_addc_co_u32_e32 v61, vcc, 0, v27, vcc
	v_mov_b32_e32 v60, v206
	v_mov_b32_e32 v61, v207
	v_cvt_f32_f16_e32 v64, v60
	v_cvt_f32_f16_sdwa v65, v60 dst_sel:DWORD dst_unused:UNUSED_PAD src0_sel:WORD_1
	v_cvt_f32_f16_e32 v62, v61
	v_cvt_f32_f16_sdwa v63, v61 dst_sel:DWORD dst_unused:UNUSED_PAD src0_sel:WORD_1
	v_pk_add_f32 v[60:61], v[58:59], v[64:65]
	v_add_co_u32_e32 v58, vcc, s0, v10
	s_mov_b32 s0, 0x1c00000
	s_nop 0
	v_addc_co_u32_e32 v59, vcc, 0, v11, vcc
	v_pk_add_f32 v[12:13], v[12:13], v[62:63]
	v_add_co_u32_e32 v62, vcc, s0, v26
	global_load_dwordx2 v[58:59], v[58:59], off
	s_nop 0
	v_addc_co_u32_e32 v63, vcc, 0, v27, vcc
	v_mov_b32_e32 v62, v208
	v_mov_b32_e32 v63, v209
	v_cvt_f32_f16_e32 v64, v62
	v_cvt_f32_f16_sdwa v65, v62 dst_sel:DWORD dst_unused:UNUSED_PAD src0_sel:WORD_1
	v_cvt_f32_f16_e32 v62, v63
	v_cvt_f32_f16_sdwa v63, v63 dst_sel:DWORD dst_unused:UNUSED_PAD src0_sel:WORD_1
	v_pk_add_f32 v[12:13], v[12:13], v[62:63]
	v_pk_add_f32 v[62:63], v[60:61], v[64:65]
	v_add_co_u32_e32 v60, vcc, s0, v10
	s_mov_b32 s0, 0x1e00000
	s_nop 0
	v_addc_co_u32_e32 v61, vcc, 0, v11, vcc
	v_add_co_u32_e32 v64, vcc, s0, v26
	global_load_dwordx2 v[60:61], v[60:61], off
	s_nop 0
	v_addc_co_u32_e32 v65, vcc, 0, v27, vcc
	v_mov_b32_e32 v64, v210
	v_mov_b32_e32 v65, v211
	v_add_co_u32_e32 v10, vcc, s0, v10
	s_ashr_i32 s0, s16, 4
	s_and_b32 s0, s0, -4
	s_add_i32 s0, s0, s4
	s_mul_hi_i32 s1, s0, 0xc000
	s_mul_i32 s0, s0, 0xc000
	s_add_u32 s0, s10, s0
	v_addc_co_u32_e32 v11, vcc, 0, v11, vcc
	s_addc_u32 s1, s11, s1
	s_waitcnt vmcnt(0)
	v_cvt_f32_f16_e32 v74, v64
	v_cvt_f32_f16_sdwa v75, v64 dst_sel:DWORD dst_unused:UNUSED_PAD src0_sel:WORD_1
	v_cvt_f32_f16_e32 v66, v65
	v_cvt_f32_f16_sdwa v67, v65 dst_sel:DWORD dst_unused:UNUSED_PAD src0_sel:WORD_1
	v_pk_add_f32 v[64:65], v[62:63], v[74:75]
	global_load_dwordx2 v[62:63], v[10:11], off
	v_lshl_add_u64 v[10:11], v[14:15], 4, s[0:1]
	v_add_co_u32_e32 v10, vcc, s73, v10
	v_pk_add_f32 v[66:67], v[12:13], v[66:67]
	s_nop 0
	v_addc_co_u32_e32 v11, vcc, 0, v11, vcc
	global_load_dwordx4 v[10:13], v[10:11], off
	s_add_i32 s0, s16, 0x2000
	s_ashr_i32 s1, s0, 31
	s_lshl_b64 s[0:1], s[0:1], 12
	s_and_b64 vcc, exec, s[40:41]
	s_waitcnt vmcnt(0)
	v_pk_fma_f32 v[8:9], v[66:67], v[12:13], v[8:9]
	v_pk_fma_f32 v[6:7], v[64:65], v[10:11], v[6:7]
	v_lshl_add_u64 v[10:11], v[20:21], 0, s[0:1]
	v_cvt_pk_f16_f32 v13, v8, v9
	v_cvt_pk_f16_f32 v12, v6, v7
	global_store_dwordx2 v[10:11], v[12:13], off
	s_cbranch_vccnz .LBB0_323
	v_cvt_f32_f16_sdwa v13, v31 dst_sel:DWORD dst_unused:UNUSED_PAD src0_sel:WORD_1
	v_cvt_f32_f16_e32 v12, v31
	v_cvt_f32_f16_sdwa v11, v30 dst_sel:DWORD dst_unused:UNUSED_PAD src0_sel:WORD_1
	v_cvt_f32_f16_e32 v10, v30
	v_cvt_f32_f16_sdwa v31, v33 dst_sel:DWORD dst_unused:UNUSED_PAD src0_sel:WORD_1
	v_cvt_f32_f16_e32 v30, v33
	v_pk_add_f32 v[12:13], v[12:13], 0 op_sel_hi:[1,0]
	v_cvt_f32_f16_sdwa v65, v32 dst_sel:DWORD dst_unused:UNUSED_PAD src0_sel:WORD_1
	v_cvt_f32_f16_e32 v64, v32
	v_pk_add_f32 v[12:13], v[12:13], v[30:31]
	v_cvt_f32_f16_sdwa v31, v36 dst_sel:DWORD dst_unused:UNUSED_PAD src0_sel:WORD_1
	v_cvt_f32_f16_e32 v30, v36
	v_pk_add_f32 v[10:11], v[10:11], 0 op_sel_hi:[1,0]
	v_cvt_f32_f16_sdwa v33, v37 dst_sel:DWORD dst_unused:UNUSED_PAD src0_sel:WORD_1
	v_pk_add_f32 v[10:11], v[10:11], v[64:65]
	v_cvt_f32_f16_e32 v32, v37
	v_pk_add_f32 v[10:11], v[10:11], v[30:31]
	v_cvt_f32_f16_sdwa v31, v39 dst_sel:DWORD dst_unused:UNUSED_PAD src0_sel:WORD_1
	v_cvt_f32_f16_e32 v30, v39
	v_pk_add_f32 v[12:13], v[12:13], v[32:33]
	v_cvt_f32_f16_sdwa v33, v38 dst_sel:DWORD dst_unused:UNUSED_PAD src0_sel:WORD_1
	v_cvt_f32_f16_e32 v32, v38
	v_pk_add_f32 v[12:13], v[12:13], v[30:31]
	v_cvt_f32_f16_sdwa v31, v40 dst_sel:DWORD dst_unused:UNUSED_PAD src0_sel:WORD_1
	v_cvt_f32_f16_e32 v30, v40
	v_pk_add_f32 v[10:11], v[10:11], v[32:33]
	v_cvt_f32_f16_sdwa v33, v41 dst_sel:DWORD dst_unused:UNUSED_PAD src0_sel:WORD_1
	v_cvt_f32_f16_e32 v32, v41
	v_pk_add_f32 v[10:11], v[10:11], v[30:31]
	v_cvt_f32_f16_sdwa v31, v43 dst_sel:DWORD dst_unused:UNUSED_PAD src0_sel:WORD_1
	v_cvt_f32_f16_e32 v30, v43
	v_pk_add_f32 v[12:13], v[12:13], v[32:33]
	v_cvt_f32_f16_sdwa v33, v42 dst_sel:DWORD dst_unused:UNUSED_PAD src0_sel:WORD_1
	v_cvt_f32_f16_e32 v32, v42
	v_pk_add_f32 v[12:13], v[12:13], v[30:31]
	v_cvt_f32_f16_sdwa v31, v44 dst_sel:DWORD dst_unused:UNUSED_PAD src0_sel:WORD_1
	v_cvt_f32_f16_e32 v30, v44
	v_pk_add_f32 v[10:11], v[10:11], v[32:33]
	v_cvt_f32_f16_sdwa v33, v45 dst_sel:DWORD dst_unused:UNUSED_PAD src0_sel:WORD_1
	v_cvt_f32_f16_e32 v32, v45
	v_pk_add_f32 v[10:11], v[10:11], v[30:31]
	v_cvt_f32_f16_sdwa v31, v47 dst_sel:DWORD dst_unused:UNUSED_PAD src0_sel:WORD_1
	v_cvt_f32_f16_e32 v30, v47
	v_pk_add_f32 v[12:13], v[12:13], v[32:33]
	v_cvt_f32_f16_sdwa v33, v46 dst_sel:DWORD dst_unused:UNUSED_PAD src0_sel:WORD_1
	v_cvt_f32_f16_e32 v32, v46
	v_pk_add_f32 v[12:13], v[12:13], v[30:31]
	v_cvt_f32_f16_sdwa v31, v48 dst_sel:DWORD dst_unused:UNUSED_PAD src0_sel:WORD_1
	v_cvt_f32_f16_e32 v30, v48
	v_pk_add_f32 v[10:11], v[10:11], v[32:33]
	v_cvt_f32_f16_sdwa v33, v49 dst_sel:DWORD dst_unused:UNUSED_PAD src0_sel:WORD_1
	v_cvt_f32_f16_e32 v32, v49
	v_pk_add_f32 v[10:11], v[10:11], v[30:31]
	v_cvt_f32_f16_sdwa v31, v51 dst_sel:DWORD dst_unused:UNUSED_PAD src0_sel:WORD_1
	v_cvt_f32_f16_e32 v30, v51
	v_pk_add_f32 v[12:13], v[12:13], v[32:33]
	v_cvt_f32_f16_sdwa v33, v50 dst_sel:DWORD dst_unused:UNUSED_PAD src0_sel:WORD_1
	v_cvt_f32_f16_e32 v32, v50
	v_pk_add_f32 v[12:13], v[12:13], v[30:31]
	v_cvt_f32_f16_sdwa v31, v52 dst_sel:DWORD dst_unused:UNUSED_PAD src0_sel:WORD_1
	v_cvt_f32_f16_e32 v30, v52
	v_pk_add_f32 v[10:11], v[10:11], v[32:33]
	v_cvt_f32_f16_sdwa v33, v53 dst_sel:DWORD dst_unused:UNUSED_PAD src0_sel:WORD_1
	v_cvt_f32_f16_e32 v32, v53
	v_pk_add_f32 v[10:11], v[10:11], v[30:31]
	v_cvt_f32_f16_sdwa v31, v55 dst_sel:DWORD dst_unused:UNUSED_PAD src0_sel:WORD_1
	v_cvt_f32_f16_e32 v30, v55
	v_pk_add_f32 v[12:13], v[12:13], v[32:33]
	v_cvt_f32_f16_sdwa v33, v54 dst_sel:DWORD dst_unused:UNUSED_PAD src0_sel:WORD_1
	v_cvt_f32_f16_e32 v32, v54
	v_pk_add_f32 v[12:13], v[12:13], v[30:31]
	v_cvt_f32_f16_sdwa v31, v56 dst_sel:DWORD dst_unused:UNUSED_PAD src0_sel:WORD_1
	v_cvt_f32_f16_e32 v30, v56
	v_pk_add_f32 v[10:11], v[10:11], v[32:33]
	v_cvt_f32_f16_sdwa v33, v57 dst_sel:DWORD dst_unused:UNUSED_PAD src0_sel:WORD_1
	v_cvt_f32_f16_e32 v32, v57
	v_pk_add_f32 v[10:11], v[10:11], v[30:31]
	v_cvt_f32_f16_sdwa v31, v59 dst_sel:DWORD dst_unused:UNUSED_PAD src0_sel:WORD_1
	v_cvt_f32_f16_e32 v30, v59
	v_pk_add_f32 v[12:13], v[12:13], v[32:33]
	v_cvt_f32_f16_sdwa v33, v58 dst_sel:DWORD dst_unused:UNUSED_PAD src0_sel:WORD_1
	v_cvt_f32_f16_e32 v32, v58
	v_pk_add_f32 v[12:13], v[12:13], v[30:31]
	v_cvt_f32_f16_sdwa v31, v60 dst_sel:DWORD dst_unused:UNUSED_PAD src0_sel:WORD_1
	v_cvt_f32_f16_e32 v30, v60
	s_ashr_i32 s0, s17, 4
	v_pk_add_f32 v[10:11], v[10:11], v[32:33]
	v_cvt_f32_f16_sdwa v33, v61 dst_sel:DWORD dst_unused:UNUSED_PAD src0_sel:WORD_1
	v_cvt_f32_f16_e32 v32, v61
	s_and_b32 s0, s0, -4
	v_pk_add_f32 v[10:11], v[10:11], v[30:31]
	v_cvt_f32_f16_sdwa v31, v62 dst_sel:DWORD dst_unused:UNUSED_PAD src0_sel:WORD_1
	v_cvt_f32_f16_e32 v30, v62
	s_add_i32 s0, s0, s4
	s_mul_hi_i32 s1, s0, 0xc000
	s_mul_i32 s0, s0, 0xc000
	s_add_u32 s0, s10, s0
	v_pk_add_f32 v[12:13], v[12:13], v[32:33]
	v_cvt_f32_f16_sdwa v33, v63 dst_sel:DWORD dst_unused:UNUSED_PAD src0_sel:WORD_1
	v_cvt_f32_f16_e32 v32, v63
	s_addc_u32 s1, s11, s1
	v_pk_add_f32 v[30:31], v[10:11], v[30:31]
	v_lshl_add_u64 v[10:11], v[14:15], 4, s[0:1]
	v_add_co_u32_e32 v10, vcc, s73, v10
	v_pk_add_f32 v[32:33], v[12:13], v[32:33]
	s_nop 0
	v_addc_co_u32_e32 v11, vcc, 0, v11, vcc
	global_load_dwordx4 v[10:13], v[10:11], off
	s_add_i32 s0, s17, 0x2000
	s_ashr_i32 s1, s0, 31
	s_lshl_b64 s[0:1], s[0:1], 12
	s_waitcnt vmcnt(0)
	v_pk_fma_f32 v[4:5], v[32:33], v[12:13], v[4:5]
	v_pk_fma_f32 v[2:3], v[30:31], v[10:11], v[2:3]
	v_lshl_add_u64 v[10:11], v[20:21], 0, s[0:1]
	v_cvt_pk_f16_f32 v13, v4, v5
	v_cvt_pk_f16_f32 v12, v2, v3
	global_store_dwordx2 v[10:11], v[12:13], off

.LBB0_904:
	s_or_b64 exec, exec, s[12:13]
	s_add_i32 s17, s17, 1
	v_cmp_lt_u32_e64 s[70:71], s17, v184
	v_lshl_add_u64 v[206:207], v[168:169], 0, v[34:35]
	s_and_saveexec_b64 s[12:13], s[70:71]
	s_cbranch_execz .LBB0_906
	v_add_co_u32_e32 v104, vcc, 0x41100000, v206
	s_nop 1
	v_addc_co_u32_e32 v105, vcc, 0, v207, vcc
	global_load_dwordx2 v[104:105], v[104:105], off
.LBB0_906:
	s_or_b64 exec, exec, s[12:13]
	s_add_i32 s17, s17, 1
	v_cmp_lt_u32_e64 s[68:69], s17, v184
	v_lshl_add_u64 v[204:205], v[166:167], 0, v[34:35]
	s_and_saveexec_b64 s[12:13], s[68:69]
	s_cbranch_execz .LBB0_908
	v_add_co_u32_e32 v102, vcc, 0x41100000, v204
	s_nop 1
	v_addc_co_u32_e32 v103, vcc, 0, v205, vcc
	global_load_dwordx2 v[102:103], v[102:103], off
.LBB0_908:
	s_or_b64 exec, exec, s[12:13]
	s_add_i32 s17, s17, 1
	v_cmp_lt_u32_e64 s[66:67], s17, v184
	v_lshl_add_u64 v[202:203], v[160:161], 0, v[34:35]
	s_and_saveexec_b64 s[12:13], s[66:67]
	s_cbranch_execz .LBB0_910
	v_add_co_u32_e32 v100, vcc, 0x41100000, v202
	s_nop 1
	v_addc_co_u32_e32 v101, vcc, 0, v203, vcc
	global_load_dwordx2 v[100:101], v[100:101], off
.LBB0_910:
	s_or_b64 exec, exec, s[12:13]
	s_add_i32 s17, s17, 1
	v_cmp_lt_u32_e64 s[64:65], s17, v184
	v_lshl_add_u64 v[200:201], v[158:159], 0, v[34:35]
	s_and_saveexec_b64 s[12:13], s[64:65]
	s_cbranch_execz .LBB0_912
	v_add_co_u32_e32 v98, vcc, 0x41100000, v200
	s_nop 1
	v_addc_co_u32_e32 v99, vcc, 0, v201, vcc
	global_load_dwordx2 v[98:99], v[98:99], off
.LBB0_912:
	s_or_b64 exec, exec, s[12:13]
	s_add_i32 s17, s17, 1
	v_cmp_lt_u32_e64 s[62:63], s17, v184
	v_lshl_add_u64 v[198:199], v[156:157], 0, v[34:35]
	s_and_saveexec_b64 s[12:13], s[62:63]
	s_cbranch_execz .LBB0_914
	v_add_co_u32_e32 v96, vcc, 0x41100000, v198
	s_nop 1
	v_addc_co_u32_e32 v97, vcc, 0, v199, vcc
	global_load_dwordx2 v[96:97], v[96:97], off
.LBB0_914:
	s_or_b64 exec, exec, s[12:13]
	s_add_i32 s17, s17, 1
	v_cmp_lt_u32_e64 s[60:61], s17, v184
	v_lshl_add_u64 v[196:197], v[154:155], 0, v[34:35]
	s_and_saveexec_b64 s[12:13], s[60:61]
	s_cbranch_execz .LBB0_916
	v_add_co_u32_e32 v94, vcc, 0x41100000, v196
	s_nop 1
	v_addc_co_u32_e32 v95, vcc, 0, v197, vcc
	global_load_dwordx2 v[94:95], v[94:95], off
.LBB0_916:
	s_or_b64 exec, exec, s[12:13]
	s_add_i32 s17, s17, 1
	v_cmp_lt_u32_e64 s[58:59], s17, v184
	v_lshl_add_u64 v[194:195], v[152:153], 0, v[34:35]
	s_and_saveexec_b64 s[12:13], s[58:59]
	s_cbranch_execz .LBB0_918
	v_add_co_u32_e32 v92, vcc, 0x41100000, v194
	s_nop 1
	v_addc_co_u32_e32 v93, vcc, 0, v195, vcc
	global_load_dwordx2 v[92:93], v[92:93], off
.LBB0_918:
	s_or_b64 exec, exec, s[12:13]
	s_add_i32 s17, s17, 1
	v_cmp_lt_u32_e64 s[56:57], s17, v184
	v_lshl_add_u64 v[192:193], v[150:151], 0, v[34:35]
	s_and_saveexec_b64 s[12:13], s[56:57]
	s_cbranch_execz .LBB0_920
	v_add_co_u32_e32 v90, vcc, 0x41100000, v192
	s_nop 1
	v_addc_co_u32_e32 v91, vcc, 0, v193, vcc
	global_load_dwordx2 v[90:91], v[90:91], off
.LBB0_920:
	s_or_b64 exec, exec, s[12:13]
	s_add_i32 s17, s17, 1
	v_cmp_lt_u32_e64 s[54:55], s17, v184
	v_lshl_add_u64 v[190:191], v[148:149], 0, v[34:35]
	s_and_saveexec_b64 s[12:13], s[54:55]
	s_cbranch_execz .LBB0_922
	v_add_co_u32_e32 v88, vcc, 0x41100000, v190
	s_nop 1
	v_addc_co_u32_e32 v89, vcc, 0, v191, vcc
	global_load_dwordx2 v[88:89], v[88:89], off
.LBB0_922:
	s_or_b64 exec, exec, s[12:13]
	s_add_i32 s17, s17, 1
	v_cmp_lt_u32_e64 s[52:53], s17, v184
	v_lshl_add_u64 v[182:183], v[146:147], 0, v[34:35]
	s_and_saveexec_b64 s[12:13], s[52:53]
	s_cbranch_execz .LBB0_924
	v_add_co_u32_e32 v86, vcc, 0x41100000, v182
	s_nop 1
	v_addc_co_u32_e32 v87, vcc, 0, v183, vcc
	global_load_dwordx2 v[86:87], v[86:87], off
.LBB0_924:
	s_or_b64 exec, exec, s[12:13]
	s_add_i32 s17, s17, 1
	v_cmp_lt_u32_e64 s[50:51], s17, v184
	v_lshl_add_u64 v[180:181], v[144:145], 0, v[34:35]
	s_and_saveexec_b64 s[12:13], s[50:51]
	s_cbranch_execz .LBB0_926
	v_add_co_u32_e32 v84, vcc, 0x41100000, v180
	s_nop 1
	v_addc_co_u32_e32 v85, vcc, 0, v181, vcc
	global_load_dwordx2 v[84:85], v[84:85], off
.LBB0_926:
	s_or_b64 exec, exec, s[12:13]
	s_add_i32 s17, s17, 1
	v_cmp_lt_u32_e64 s[48:49], s17, v184
	v_lshl_add_u64 v[178:179], v[142:143], 0, v[34:35]
	s_and_saveexec_b64 s[12:13], s[48:49]
	s_cbranch_execz .LBB0_928
	v_add_co_u32_e32 v82, vcc, 0x41100000, v178
	s_nop 1
	v_addc_co_u32_e32 v83, vcc, 0, v179, vcc
	global_load_dwordx2 v[82:83], v[82:83], off
.LBB0_928:
	s_or_b64 exec, exec, s[12:13]
	s_add_i32 s17, s17, 1
	v_cmp_lt_u32_e64 s[46:47], s17, v184
	v_lshl_add_u64 v[176:177], v[140:141], 0, v[34:35]
	s_and_saveexec_b64 s[12:13], s[46:47]
	s_cbranch_execz .LBB0_930
	v_add_co_u32_e32 v80, vcc, 0x41100000, v176
	s_nop 1
	v_addc_co_u32_e32 v81, vcc, 0, v177, vcc
	global_load_dwordx2 v[80:81], v[80:81], off
.LBB0_930:
	s_or_b64 exec, exec, s[12:13]
	s_add_i32 s17, s17, 1
	v_cmp_lt_u32_e64 s[44:45], s17, v184
	v_lshl_add_u64 v[174:175], v[138:139], 0, v[34:35]
	s_and_saveexec_b64 s[12:13], s[44:45]
	s_cbranch_execz .LBB0_932
	v_add_co_u32_e32 v78, vcc, 0x41100000, v174
	s_nop 1
	v_addc_co_u32_e32 v79, vcc, 0, v175, vcc
	global_load_dwordx2 v[78:79], v[78:79], off

.LBB0_949:
	s_waitcnt vmcnt(0)
	s_or_b64 exec, exec, s[12:13]
	s_and_saveexec_b64 s[12:13], s[72:73]
	s_cbranch_execz .LBB0_934

.LBB0_980:
	s_or_b64 exec, exec, s[12:13]
	s_add_i32 s17, s17, 1
	v_cmp_lt_u32_e64 s[42:43], s17, v184
	v_lshl_add_u64 v[212:213], s[26:27], 0, v[170:171]
	s_and_saveexec_b64 s[12:13], s[42:43]
	s_cbranch_execz .LBB0_982
	v_add_co_u32_e32 v62, vcc, 0x3e800000, v212
	v_lshl_add_u64 v[64:65], s[26:27], 0, v[208:209]
	s_nop 0
	v_addc_co_u32_e32 v63, vcc, 0, v213, vcc
	global_load_dwordx2 v[108:109], v[62:63], off
	s_nop 0
	global_load_dwordx4 v[62:65], v[64:65], off
.LBB0_982:
	s_or_b64 exec, exec, s[12:13]
	s_add_i32 s17, s17, 1
	v_cmp_lt_u32_e64 s[44:45], s17, v184
	v_lshl_add_u64 v[214:215], s[26:27], 0, v[168:169]
	s_and_saveexec_b64 s[12:13], s[44:45]
	s_cbranch_execz .LBB0_984
	v_add_co_u32_e32 v58, vcc, 0x3e800000, v214
	v_lshl_add_u64 v[60:61], s[26:27], 0, v[206:207]
	s_nop 0
	v_addc_co_u32_e32 v59, vcc, 0, v215, vcc
	global_load_dwordx2 v[110:111], v[58:59], off
	s_nop 0
	global_load_dwordx4 v[58:61], v[60:61], off
.LBB0_984:
	s_or_b64 exec, exec, s[12:13]
	s_add_i32 s17, s17, 1
	v_cmp_lt_u32_e64 s[46:47], s17, v184
	v_lshl_add_u64 v[216:217], s[26:27], 0, v[166:167]
	s_and_saveexec_b64 s[12:13], s[46:47]
	s_cbranch_execz .LBB0_986
	v_add_co_u32_e32 v54, vcc, 0x3e800000, v216
	v_lshl_add_u64 v[56:57], s[26:27], 0, v[204:205]
	s_nop 0
	v_addc_co_u32_e32 v55, vcc, 0, v217, vcc
	global_load_dwordx2 v[112:113], v[54:55], off
	s_nop 0
	global_load_dwordx4 v[54:57], v[56:57], off
.LBB0_986:
	s_or_b64 exec, exec, s[12:13]
	s_add_i32 s17, s17, 1
	v_cmp_lt_u32_e64 s[48:49], s17, v184
	v_lshl_add_u64 v[218:219], s[26:27], 0, v[164:165]
	s_and_saveexec_b64 s[12:13], s[48:49]
	s_cbranch_execz .LBB0_988
	v_add_co_u32_e32 v50, vcc, 0x3e800000, v218
	v_lshl_add_u64 v[52:53], s[26:27], 0, v[202:203]
	s_nop 0
	v_addc_co_u32_e32 v51, vcc, 0, v219, vcc
	global_load_dwordx2 v[114:115], v[50:51], off
	s_nop 0
	global_load_dwordx4 v[50:53], v[52:53], off
.LBB0_988:
	s_or_b64 exec, exec, s[12:13]
	s_add_i32 s17, s17, 1
	v_cmp_lt_u32_e64 s[50:51], s17, v184
	v_lshl_add_u64 v[220:221], s[26:27], 0, v[162:163]
	s_and_saveexec_b64 s[12:13], s[50:51]
	s_cbranch_execz .LBB0_990
	v_add_co_u32_e32 v46, vcc, 0x3e800000, v220
	v_lshl_add_u64 v[48:49], s[26:27], 0, v[200:201]
	s_nop 0
	v_addc_co_u32_e32 v47, vcc, 0, v221, vcc
	global_load_dwordx2 v[116:117], v[46:47], off
	s_nop 0
	global_load_dwordx4 v[46:49], v[48:49], off
.LBB0_990:
	s_or_b64 exec, exec, s[12:13]
	s_add_i32 s17, s17, 1
	v_cmp_lt_u32_e64 s[52:53], s17, v184
	v_lshl_add_u64 v[222:223], s[26:27], 0, v[160:161]
	s_and_saveexec_b64 s[12:13], s[52:53]
	s_cbranch_execz .LBB0_992
	v_add_co_u32_e32 v42, vcc, 0x3e800000, v222
	v_lshl_add_u64 v[44:45], s[26:27], 0, v[198:199]
	s_nop 0
	v_addc_co_u32_e32 v43, vcc, 0, v223, vcc
	global_load_dwordx2 v[118:119], v[42:43], off
	s_nop 0
	global_load_dwordx4 v[42:45], v[44:45], off
.LBB0_992:
	s_or_b64 exec, exec, s[12:13]
	s_add_i32 s17, s17, 1
	v_cmp_lt_u32_e64 s[54:55], s17, v184
	v_lshl_add_u64 v[224:225], s[26:27], 0, v[158:159]
	s_and_saveexec_b64 s[12:13], s[54:55]
	s_cbranch_execz .LBB0_994
	v_add_co_u32_e32 v38, vcc, 0x3e800000, v224
	v_lshl_add_u64 v[40:41], s[26:27], 0, v[196:197]
	s_nop 0
	v_addc_co_u32_e32 v39, vcc, 0, v225, vcc
	global_load_dwordx2 v[120:121], v[38:39], off
	s_nop 0
	global_load_dwordx4 v[38:41], v[40:41], off
.LBB0_994:
	s_or_b64 exec, exec, s[12:13]
	s_add_i32 s17, s17, 1
	v_cmp_lt_u32_e64 s[56:57], s17, v184
	v_lshl_add_u64 v[226:227], s[26:27], 0, v[156:157]
	s_and_saveexec_b64 s[12:13], s[56:57]
	s_cbranch_execz .LBB0_996
	v_add_co_u32_e32 v30, vcc, 0x3e800000, v226
	v_lshl_add_u64 v[32:33], s[26:27], 0, v[194:195]
	s_nop 0
	v_addc_co_u32_e32 v31, vcc, 0, v227, vcc
	global_load_dwordx2 v[122:123], v[30:31], off
	s_nop 0
	global_load_dwordx4 v[30:33], v[32:33], off
.LBB0_996:
	s_or_b64 exec, exec, s[12:13]
	s_add_i32 s17, s17, 1
	v_cmp_lt_u32_e64 s[58:59], s17, v184
	v_lshl_add_u64 v[228:229], s[26:27], 0, v[154:155]
	s_and_saveexec_b64 s[12:13], s[58:59]
	s_cbranch_execz .LBB0_998
	v_add_co_u32_e32 v26, vcc, 0x3e800000, v228
	v_lshl_add_u64 v[28:29], s[26:27], 0, v[192:193]
	s_nop 0
	v_addc_co_u32_e32 v27, vcc, 0, v229, vcc
	global_load_dwordx2 v[124:125], v[26:27], off
	s_nop 0
	global_load_dwordx4 v[26:29], v[28:29], off
.LBB0_998:
	s_or_b64 exec, exec, s[12:13]
	s_add_i32 s17, s17, 1
	v_cmp_lt_u32_e64 s[60:61], s17, v184
	v_lshl_add_u64 v[230:231], s[26:27], 0, v[152:153]
	s_and_saveexec_b64 s[12:13], s[60:61]
	s_cbranch_execz .LBB0_1000
	v_add_co_u32_e32 v22, vcc, 0x3e800000, v230
	v_lshl_add_u64 v[24:25], s[26:27], 0, v[190:191]
	s_nop 0
	v_addc_co_u32_e32 v23, vcc, 0, v231, vcc
	global_load_dwordx2 v[126:127], v[22:23], off
	s_nop 0
	global_load_dwordx4 v[22:25], v[24:25], off
.LBB0_1000:
	s_or_b64 exec, exec, s[12:13]
	s_add_i32 s17, s17, 1
	v_cmp_lt_u32_e64 s[62:63], s17, v184
	v_lshl_add_u64 v[232:233], s[26:27], 0, v[150:151]
	s_and_saveexec_b64 s[12:13], s[62:63]
	s_cbranch_execz .LBB0_1002
	v_add_co_u32_e32 v18, vcc, 0x3e800000, v232
	v_lshl_add_u64 v[20:21], s[26:27], 0, v[182:183]
	s_nop 0
	v_addc_co_u32_e32 v19, vcc, 0, v233, vcc
	global_load_dwordx2 v[128:129], v[18:19], off
	s_nop 0
	global_load_dwordx4 v[18:21], v[20:21], off
.LBB0_1002:
	s_or_b64 exec, exec, s[12:13]
	s_add_i32 s17, s17, 1
	v_cmp_lt_u32_e64 s[64:65], s17, v184
	v_lshl_add_u64 v[234:235], s[26:27], 0, v[148:149]
	s_and_saveexec_b64 s[12:13], s[64:65]
	s_cbranch_execz .LBB0_1004
	v_add_co_u32_e32 v14, vcc, 0x3e800000, v234
	v_lshl_add_u64 v[16:17], s[26:27], 0, v[180:181]
	s_nop 0
	v_addc_co_u32_e32 v15, vcc, 0, v235, vcc
	global_load_dwordx2 v[130:131], v[14:15], off
	s_nop 0
	global_load_dwordx4 v[14:17], v[16:17], off
.LBB0_1004:
	s_or_b64 exec, exec, s[12:13]
	s_add_i32 s17, s17, 1
	v_cmp_lt_u32_e64 s[66:67], s17, v184
	v_lshl_add_u64 v[236:237], s[26:27], 0, v[146:147]
	s_and_saveexec_b64 s[12:13], s[66:67]
	s_cbranch_execz .LBB0_1006
	v_add_co_u32_e32 v10, vcc, 0x3e800000, v236
	v_lshl_add_u64 v[12:13], s[26:27], 0, v[178:179]
	s_nop 0
	v_addc_co_u32_e32 v11, vcc, 0, v237, vcc
	global_load_dwordx2 v[132:133], v[10:11], off
	s_nop 0
	global_load_dwordx4 v[10:13], v[12:13], off
.LBB0_1006:
	s_or_b64 exec, exec, s[12:13]
	s_add_i32 s17, s17, 1
	v_cmp_lt_u32_e64 s[68:69], s17, v184
	v_lshl_add_u64 v[238:239], s[26:27], 0, v[144:145]
	s_and_saveexec_b64 s[12:13], s[68:69]
	s_cbranch_execz .LBB0_1008
	v_add_co_u32_e32 v6, vcc, 0x3e800000, v238
	v_lshl_add_u64 v[8:9], s[26:27], 0, v[176:177]
	s_nop 0
	v_addc_co_u32_e32 v7, vcc, 0, v239, vcc
	global_load_dwordx2 v[134:135], v[6:7], off
	s_nop 0
	global_load_dwordx4 v[6:9], v[8:9], off

.LBB0_1025:
	s_waitcnt vmcnt(0)
	s_or_b64 exec, exec, s[12:13]
	s_and_saveexec_b64 s[12:13], s[40:41]
	s_cbranch_execz .LBB0_1010
